# prologue: pool-fold items split into quarters (512 quarter items on 4x the waves) - removes the fold critical-path pole
# speedup vs baseline: 1.0084x; 1.0042x over previous
.LBB0_17:
	s_cmp_lt_i32 s84, 1
	s_cselect_b64 s[12:13], -1, 0
	s_cmp_gt_i32 s85, 0
	s_cselect_b64 s[4:5], -1, 0
	s_and_b64 s[4:5], s[12:13], s[4:5]
	v_writelane_b32 v253, s84, 2
	s_andn2_b64 vcc, exec, s[4:5]
	s_nop 0
	v_writelane_b32 v253, s85, 3
	s_cbranch_vccnz .LBB0_48
	v_mov_b32_e32 v1, v204
	v_writelane_b32 v253, s50, 4
	s_lshl_b32 s3, s2, 3
	v_ashrrev_i32_e32 v0, 6, v1
	s_mov_b64 s[16:17], s[76:77]
	v_writelane_b32 v253, s3, 6
	v_add_u32_e32 v196, s3, v0
	s_lshl_b32 s14, s70, 3
	s_movk_i32 s4, 0xd00
	v_cmp_gt_i32_e32 vcc, s4, v196
	s_mov_b64 s[4:5], exec
	v_writelane_b32 v253, s4, 8
	s_nop 1
	v_writelane_b32 v253, s5, 9
	s_and_b64 s[4:5], s[4:5], vcc
	s_mov_b64 exec, s[4:5]
	s_cbranch_execz .LBB0_42
	v_and_b32_e32 v197, 63, v1
	v_bfe_u32 v198, v1, 3, 3
	v_lshlrev_b32_e32 v2, 2, v1
	v_lshlrev_b32_e32 v1, 3, v1
	v_and_b32_e32 v1, 56, v1
	v_lshl_add_u32 v3, v0, 14, 0
	v_and_b32_e32 v2, 28, v2
	v_mov_b32_e32 v53, 0
	v_mul_u32_u24_e32 v4, 0x84, v1
	v_lshlrev_b32_e32 v5, 2, v198
	v_lshlrev_b32_e32 v52, 1, v1
	v_lshl_add_u32 v6, v2, 2, v3
	v_mul_u32_u24_e32 v7, 0x84, v198
	v_add3_u32 v207, v3, v4, v5
	v_lshl_add_u64 v[4:5], s[0:1], 0, v[52:53]
	s_mov_b64 s[4:5], 0x100000
	s_add_u32 s18, s0, 0x1600000
	v_lshlrev_b32_e32 v1, 10, v197
	v_lshlrev_b32_e32 v0, 6, v0
	v_or_b32_e32 v199, 8, v198
	v_or_b32_e32 v200, 16, v198
	v_or_b32_e32 v201, 24, v198
	v_or_b32_e32 v202, 32, v198
	v_or_b32_e32 v203, 40, v198
	v_or_b32_e32 v205, 48, v198
	v_or_b32_e32 v206, 56, v198
	v_lshl_add_u64 v[54:55], v[4:5], 0, s[4:5]
	s_addc_u32 s19, s1, 0
	v_lshl_add_u32 v208, s2, 9, v0
	s_lshl_b32 s15, s70, 9
	v_lshlrev_b32_e32 v56, 2, v2
	s_movk_i32 s26, 0x5800
	v_add_u32_e32 v209, v6, v7
	s_movk_i32 s27, 0x7fff
	s_mov_b32 s28, 0xffff0000
	v_lshlrev_b32_e32 v210, 1, v1
	s_mov_b32 s29, 0x3f000
	s_mov_b32 s30, 0x3e000
	s_mov_b32 s31, 0x3d000
	s_mov_b32 s33, 0x3c000
	s_mov_b32 s34, 0x3b000
	s_mov_b32 s35, 0x3a000
	s_mov_b32 s36, 0x39000
	s_mov_b32 s37, 0x38000
	s_mov_b32 s38, 0x37000
	s_mov_b32 s39, 0x36000
	s_mov_b32 s40, 0x35000
	s_mov_b32 s41, 0x34000
	s_mov_b32 s42, 0x33000
	s_mov_b32 s43, 0x32000
	s_mov_b32 s44, 0x31000
	s_mov_b32 s45, 0x30000
	s_mov_b32 s46, 0x2f000
	s_mov_b32 s47, 0x2e000
	s_mov_b32 s48, 0x2d000
	s_mov_b32 s49, 0x2c000
	s_mov_b32 s52, 0x2b000
	s_mov_b32 s53, 0x2a000
	s_mov_b32 s54, 0x29000
	s_mov_b32 s55, 0x28000
	s_mov_b32 s56, 0x27000
	s_mov_b32 s57, 0x26000
	s_mov_b32 s58, 0x25000
	s_mov_b32 s59, 0x24000
	s_mov_b32 s60, 0x23000
	s_mov_b32 s61, 0x22000
	s_mov_b32 s62, 0x21000
	s_mov_b32 s63, 0x20000
	s_mov_b32 s64, 0x1f000
	s_mov_b32 s65, 0x1e000
	s_mov_b32 s66, 0x1d000
	s_mov_b32 s67, 0x1c000
	s_mov_b32 s68, 0x1b000
	s_mov_b32 s69, 0x1a000
	s_mov_b32 s72, 0x19000
	s_mov_b32 s73, 0x18000
	s_mov_b32 s74, 0x17000
	s_mov_b32 s75, 0x16000
	s_mov_b32 s50, 0x15000
	s_mov_b32 s3, 0x14000
	s_mov_b32 s78, 0x13000
	s_mov_b32 s79, 0x12000
	s_mov_b32 s80, 0x11000
	s_mov_b32 s81, 0x10000
	s_mov_b32 s82, 0xf000
	s_mov_b32 s83, 0xe000
	s_mov_b32 s84, 0xd000
	s_mov_b32 s85, 0xc000
	s_mov_b32 s86, 0xb000
	s_mov_b32 s87, 0xa000
	s_mov_b32 s88, 0x9000
	s_mov_b32 s89, 0x8000
	s_movk_i32 s90, 0x7000
	s_movk_i32 s91, 0x6000
	s_movk_i32 s92, 0x5000
	v_mov_b32_e32 v211, 1
	s_movk_i32 s93, 0x4000
	s_movk_i32 s94, 0x3000
	s_movk_i32 s95, 0x2000
	s_movk_i32 s96, 0x1000
	s_movk_i32 s97, 0xcff
	s_mov_b32 s21, 0
	s_mov_b64 s[22:23], 0
	s_branch .LBB0_21

.LBB0_21:
	s_movk_i32 s4, 0x1ff
	v_cmp_lt_i32_e32 vcc, s4, v196
	s_and_saveexec_b64 s[4:5], vcc
	s_xor_b64 s[6:7], exec, s[4:5]
	s_cbranch_execz .LBB0_39
	v_add_u16_e32 v0, 0xfe00, v196
	v_mul_u32_u24_e32 v1, 0xba2f, v0
	v_lshrrev_b32_e32 v1, 23, v1
	v_mul_lo_u16_e32 v2, 0xb0, v1
	v_sub_u16_e32 v0, v0, v2
	v_lshlrev_b32_e32 v6, 5, v0
	v_lshlrev_b32_e32 v0, 4, v0
	s_load_dwordx4 s[8:11], s[16:17], 0x38
	v_and_b32_e32 v2, 0xe0, v6
	v_and_b32_e32 v0, 0xf80, v0
	s_movk_i32 s4, 0xa80
	v_or_b32_e32 v3, v0, v2
	v_add3_u32 v0, v2, v0, s4
	s_movk_i32 s4, 0x80
	v_cmp_gt_u32_e32 vcc, s4, v2
	v_lshlrev_b16_e32 v7, 6, v1
	v_mov_b32_e32 v57, v53
	v_cndmask_b32_e32 v0, v0, v3, vcc
	v_lshlrev_b32_e32 v52, 2, v0
	s_waitcnt lgkmcnt(0)
	v_lshl_add_u64 v[0:1], s[10:11], 0, v[52:53]
	v_lshl_add_u64 v[4:5], v[0:1], 0, v[56:57]
	v_or_b32_e32 v8, v198, v7
	v_mad_u64_u32 v[0:1], s[4:5], v8, s26, v[4:5]
	global_load_dwordx4 v[0:3], v[0:1], off
	s_cmp_lg_u64 s[8:9], 0
	s_cselect_b64 s[10:11], -1, 0
	s_cmp_eq_u64 s[8:9], 0
	s_cbranch_scc1 .LBB0_24
	v_lshlrev_b32_e32 v8, 2, v8
	global_load_dword v8, v8, s[8:9]
	s_waitcnt vmcnt(0)
	v_pk_mul_f32 v[2:3], v[2:3], v[8:9] op_sel_hi:[1,0]
	v_pk_mul_f32 v[0:1], v[0:1], v[8:9] op_sel_hi:[1,0]

.LBB0_39:
	s_andn2_saveexec_b64 s[8:9], s[6:7]
	s_cbranch_execz .LBB0_20
	v_lshlrev_b32_e32 v0, 4, v196
	s_movk_i32 s10, 0x3c0
	s_load_dwordx4 s[4:7], s[16:17], 0x60
	v_and_or_b32 v6, v0, s10, v197
	s_load_dwordx2 s[10:11], s[16:17], 0x70
	v_ashrrev_i32_e32 v28, 8, v196
	v_lshlrev_b32_e32 v2, 8, v28
	v_bfe_u32 v34, v196, 6, 2
	v_ashrrev_i32_e32 v3, 31, v2
	v_ashrrev_i32_e32 v29, 31, v28
	s_waitcnt lgkmcnt(0)
	v_lshl_add_u64 v[2:3], v[2:3], 2, s[10:11]
	v_lshlrev_b32_e32 v4, 8, v34
	v_mov_b32_e32 v5, v53
	v_lshlrev_b64 v[0:1], 22, v[28:29]
	v_lshl_add_u64 v[32:33], v[2:3], 0, v[4:5]
	v_lshlrev_b32_e32 v2, 2, v6
	v_lshl_add_u64 v[0:1], s[4:5], 0, v[0:1]
	v_lshl_or_b32 v2, v34, 18, v2
	v_mov_b32_e32 v3, v53
	v_lshl_add_u64 v[30:31], v[0:1], 0, v[2:3]
	v_add_co_u32_e32 v16, vcc, s29, v30
	global_load_dwordx4 v[0:3], v[32:33], off offset:192
	global_load_dwordx4 v[4:7], v[32:33], off offset:208
	global_load_dwordx4 v[8:11], v[32:33], off offset:224
	global_load_dwordx4 v[12:15], v[32:33], off offset:240
	v_addc_co_u32_e32 v17, vcc, 0, v31, vcc
	v_add_co_u32_e32 v18, vcc, s30, v30
	s_mov_b32 s4, 0x1e0000
	s_nop 0
	v_addc_co_u32_e32 v19, vcc, 0, v31, vcc
	v_add_co_u32_e32 v20, vcc, s31, v30
	v_readfirstlane_b32 s11, v196
	s_and_b32 s11, s11, 3
	s_lshl_b32 s11, s11, 4
	s_add_u32 s10, s11, 2
	s_nop 0
	v_addc_co_u32_e32 v21, vcc, 0, v31, vcc
	v_add_co_u32_e32 v22, vcc, s33, v30
	s_nop 1
	v_addc_co_u32_e32 v23, vcc, 0, v31, vcc
	v_add_co_u32_e32 v24, vcc, s34, v30
	s_nop 1
	v_addc_co_u32_e32 v25, vcc, 0, v31, vcc
	v_add_co_u32_e32 v26, vcc, s35, v30
	s_nop 1
	v_addc_co_u32_e32 v27, vcc, 0, v31, vcc
	v_add_co_u32_e32 v40, vcc, s36, v30
	s_nop 1
	v_addc_co_u32_e32 v41, vcc, 0, v31, vcc
	global_load_dword v29, v[16:17], off
	global_load_dword v35, v[18:19], off
	global_load_dword v36, v[20:21], off
	global_load_dword v37, v[22:23], off
	global_load_dword v38, v[24:25], off
	global_load_dword v39, v[26:27], off
	s_nop 0
	global_load_dword v40, v[40:41], off
	v_add_co_u32_e32 v16, vcc, s37, v30
	s_nop 1
	v_addc_co_u32_e32 v17, vcc, 0, v31, vcc
	v_add_co_u32_e32 v18, vcc, s38, v30
	s_nop 1
	v_addc_co_u32_e32 v19, vcc, 0, v31, vcc
	v_add_co_u32_e32 v20, vcc, s39, v30
	s_nop 1
	v_addc_co_u32_e32 v21, vcc, 0, v31, vcc
	v_add_co_u32_e32 v22, vcc, s40, v30
	s_nop 1
	v_addc_co_u32_e32 v23, vcc, 0, v31, vcc
	v_add_co_u32_e32 v24, vcc, s41, v30
	s_nop 1
	v_addc_co_u32_e32 v25, vcc, 0, v31, vcc
	v_add_co_u32_e32 v26, vcc, s42, v30
	s_nop 1
	v_addc_co_u32_e32 v27, vcc, 0, v31, vcc
	v_add_co_u32_e32 v48, vcc, s43, v30
	s_nop 1
	v_addc_co_u32_e32 v49, vcc, 0, v31, vcc
	v_add_co_u32_e32 v50, vcc, s44, v30
	s_nop 1
	v_addc_co_u32_e32 v51, vcc, 0, v31, vcc
	global_load_dword v41, v[16:17], off
	global_load_dword v42, v[18:19], off
	global_load_dword v43, v[20:21], off
	global_load_dword v44, v[22:23], off
	global_load_dword v45, v[24:25], off
	global_load_dword v46, v[26:27], off
	global_load_dword v47, v[48:49], off
	s_nop 0
	global_load_dword v48, v[50:51], off
	v_add_co_u32_e32 v20, vcc, s45, v30
	global_load_dwordx4 v[16:19], v[32:33], off offset:176
	s_nop 0
	v_addc_co_u32_e32 v21, vcc, 0, v31, vcc
	v_add_co_u32_e32 v22, vcc, s46, v30
	s_waitcnt vmcnt(7)
	v_mul_f32_e32 v74, v7, v42
	v_addc_co_u32_e32 v23, vcc, 0, v31, vcc
	v_add_co_u32_e32 v24, vcc, s47, v30
	s_waitcnt vmcnt(3)
	v_mul_f32_e32 v82, v3, v46
	v_addc_co_u32_e32 v25, vcc, 0, v31, vcc
	v_add_co_u32_e32 v26, vcc, s48, v30
	s_waitcnt vmcnt(2)
	v_mul_f32_e32 v84, v2, v47
	v_addc_co_u32_e32 v27, vcc, 0, v31, vcc
	v_add_co_u32_e32 v58, vcc, s49, v30
	s_waitcnt vmcnt(1)
	v_mul_f32_e32 v86, v1, v48
	v_addc_co_u32_e32 v59, vcc, 0, v31, vcc
	global_load_dword v49, v[20:21], off
	global_load_dword v50, v[22:23], off
	global_load_dword v51, v[24:25], off
	global_load_dword v52, v[26:27], off
	global_load_dword v57, v[58:59], off
	v_add_co_u32_e32 v20, vcc, s52, v30
	v_mul_f32_e32 v76, v6, v43
	s_nop 0
	v_addc_co_u32_e32 v21, vcc, 0, v31, vcc
	v_add_co_u32_e32 v22, vcc, s53, v30
	v_mul_f32_e32 v78, v5, v44
	s_nop 0
	v_addc_co_u32_e32 v23, vcc, 0, v31, vcc
	v_add_co_u32_e32 v24, vcc, s54, v30
	v_mul_f32_e32 v80, v4, v45
	s_nop 0
	v_addc_co_u32_e32 v25, vcc, 0, v31, vcc
	global_load_dword v75, v[20:21], off
	global_load_dword v77, v[22:23], off
	global_load_dword v79, v[24:25], off
	v_add_co_u32_e32 v20, vcc, s55, v30
	s_waitcnt vmcnt(7)
	v_mul_f32_e32 v88, v0, v49
	v_addc_co_u32_e32 v21, vcc, 0, v31, vcc
	v_add_co_u32_e32 v22, vcc, s56, v30
	v_lshlrev_b32_e32 v0, 9, v208
	s_nop 0
	v_addc_co_u32_e32 v23, vcc, 0, v31, vcc
	v_add_co_u32_e32 v24, vcc, s57, v30
	s_waitcnt vmcnt(4)
	v_mul_f32_e32 v94, v17, v52
	v_addc_co_u32_e32 v25, vcc, 0, v31, vcc
	v_add_co_u32_e32 v26, vcc, s58, v30
	v_and_or_b32 v52, v0, s4, v210
	s_nop 0
	v_addc_co_u32_e32 v27, vcc, 0, v31, vcc
	v_add_co_u32_e32 v58, vcc, s59, v30
	v_lshl_or_b32 v0, v28, 2, v34
	s_nop 0
	v_addc_co_u32_e32 v59, vcc, 0, v31, vcc
	global_load_dword v81, v[20:21], off
	global_load_dword v83, v[22:23], off
	global_load_dword v85, v[24:25], off
	global_load_dword v87, v[26:27], off
	global_load_dword v89, v[58:59], off
	v_add_co_u32_e32 v20, vcc, s60, v30
	s_mov_b32 s4, 0x2800000
	s_nop 0
	v_addc_co_u32_e32 v21, vcc, 0, v31, vcc
	v_add_co_u32_e32 v22, vcc, s61, v30
	v_mad_i64_i32 v[2:3], s[4:5], v28, s4, 0
	s_nop 0
	v_addc_co_u32_e32 v23, vcc, 0, v31, vcc
	v_add_co_u32_e32 v24, vcc, s62, v30
	v_ashrrev_i32_e32 v1, 31, v0
	s_nop 0
	v_addc_co_u32_e32 v25, vcc, 0, v31, vcc
	v_add_co_u32_e32 v58, vcc, s63, v30
	global_load_dword v91, v[20:21], off
	global_load_dword v93, v[22:23], off
	global_load_dword v95, v[24:25], off
	s_nop 0
	global_load_dwordx4 v[24:27], v[32:33], off offset:160
	global_load_dwordx4 v[20:23], v[32:33], off offset:144
	v_addc_co_u32_e32 v59, vcc, 0, v31, vcc
	global_load_dword v97, v[58:59], off
	v_add_co_u32_e32 v58, vcc, s64, v30
	v_lshl_or_b32 v2, v34, 7, v2
	s_nop 0
	v_addc_co_u32_e32 v59, vcc, 0, v31, vcc
	global_load_dword v99, v[58:59], off
	v_add_co_u32_e32 v58, vcc, s65, v30
	v_lshlrev_b64 v[0:1], 14, v[0:1]
	s_nop 0
	v_addc_co_u32_e32 v59, vcc, 0, v31, vcc
	global_load_dword v101, v[58:59], off
	v_add_co_u32_e32 v58, vcc, s66, v30
	v_mul_f32_e32 v90, v19, v50
	s_nop 0
	v_addc_co_u32_e32 v59, vcc, 0, v31, vcc
	global_load_dword v103, v[58:59], off
	v_add_co_u32_e32 v58, vcc, s67, v30
	v_mul_f32_e32 v92, v18, v51
	s_nop 0
	v_addc_co_u32_e32 v59, vcc, 0, v31, vcc
	global_load_dword v105, v[58:59], off
	v_add_co_u32_e32 v58, vcc, s68, v30
	s_waitcnt vmcnt(18)
	v_mul_f32_e32 v96, v16, v57
	v_addc_co_u32_e32 v59, vcc, 0, v31, vcc
	global_load_dword v107, v[58:59], off
	v_add_co_u32_e32 v58, vcc, s69, v30
	s_lshl_b32 s4, s11, 1
	s_mov_b32 s5, 0
	s_nop 0
	v_addc_co_u32_e32 v59, vcc, 0, v31, vcc
	global_load_dword v109, v[58:59], off
	v_add_co_u32_e32 v58, vcc, s72, v30
	s_waitcnt vmcnt(8)
	v_mul_f32_e32 v98, v27, v75
	v_addc_co_u32_e32 v59, vcc, 0, v31, vcc
	global_load_dword v111, v[58:59], off
	global_load_dwordx4 v[120:123], v[32:33], off offset:128
	global_load_dwordx4 v[128:131], v[32:33], off offset:112
	v_add_co_u32_e32 v58, vcc, s73, v30
	v_mul_f32_e32 v100, v26, v77
	s_nop 0
	v_addc_co_u32_e32 v59, vcc, 0, v31, vcc
	global_load_dword v113, v[58:59], off
	v_add_co_u32_e32 v58, vcc, s74, v30
	v_mul_f32_e32 v102, v25, v79
	s_nop 0
	v_addc_co_u32_e32 v59, vcc, 0, v31, vcc
	global_load_dword v115, v[58:59], off
	v_add_co_u32_e32 v58, vcc, s75, v30
	v_mul_f32_e32 v104, v24, v81
	s_nop 0
	v_addc_co_u32_e32 v59, vcc, 0, v31, vcc
	global_load_dword v117, v[58:59], off
	v_add_co_u32_e32 v58, vcc, s50, v30
	s_waitcnt vmcnt(13)
	v_mul_f32_e32 v106, v23, v83
	v_addc_co_u32_e32 v59, vcc, 0, v31, vcc
	global_load_dword v119, v[58:59], off
	v_add_co_u32_e32 v58, vcc, s3, v30
	v_mul_f32_e32 v108, v22, v85
	s_nop 0
	v_addc_co_u32_e32 v59, vcc, 0, v31, vcc
	global_load_dword v125, v[58:59], off
	v_add_co_u32_e32 v58, vcc, s78, v30
	v_mul_f32_e32 v110, v21, v87
	s_nop 0
	v_addc_co_u32_e32 v59, vcc, 0, v31, vcc
	global_load_dword v127, v[58:59], off
	v_add_co_u32_e32 v58, vcc, s79, v30
	v_mul_f32_e32 v112, v20, v89
	s_nop 0
	v_addc_co_u32_e32 v59, vcc, 0, v31, vcc
	global_load_dword v133, v[58:59], off
	v_add_co_u32_e32 v58, vcc, s80, v30
	v_mov_b32_e32 v89, v88
	s_nop 0
	v_addc_co_u32_e32 v59, vcc, 0, v31, vcc
	global_load_dword v135, v[58:59], off
	global_load_dwordx4 v[136:139], v[32:33], off offset:96
	global_load_dwordx4 v[144:147], v[32:33], off offset:80
	v_add_co_u32_e32 v58, vcc, s81, v30
	v_mov_b32_e32 v87, v86
	s_nop 0
	v_addc_co_u32_e32 v59, vcc, 0, v31, vcc
	global_load_dword v141, v[58:59], off
	v_add_co_u32_e32 v58, vcc, s82, v30
	v_mov_b32_e32 v85, v84
	s_nop 0
	v_addc_co_u32_e32 v59, vcc, 0, v31, vcc
	global_load_dword v143, v[58:59], off
	v_add_co_u32_e32 v58, vcc, s83, v30
	v_mov_b32_e32 v83, v82
	s_nop 0
	v_addc_co_u32_e32 v59, vcc, 0, v31, vcc
	global_load_dword v149, v[58:59], off
	v_add_co_u32_e32 v58, vcc, s84, v30
	v_mov_b32_e32 v81, v80
	s_nop 0
	v_addc_co_u32_e32 v59, vcc, 0, v31, vcc
	global_load_dword v151, v[58:59], off
	v_add_co_u32_e32 v58, vcc, s85, v30
	v_mov_b32_e32 v79, v78
	s_nop 0
	v_addc_co_u32_e32 v59, vcc, 0, v31, vcc
	global_load_dword v157, v[58:59], off
	v_add_co_u32_e32 v58, vcc, s86, v30
	s_waitcnt vmcnt(16)
	v_mul_f32_e32 v114, v123, v91
	v_addc_co_u32_e32 v59, vcc, 0, v31, vcc
	global_load_dword v159, v[58:59], off
	v_add_co_u32_e32 v58, vcc, s87, v30
	v_mul_f32_e32 v116, v122, v93
	s_nop 0
	v_addc_co_u32_e32 v59, vcc, 0, v31, vcc
	global_load_dword v164, v[58:59], off
	v_add_co_u32_e32 v58, vcc, s88, v30
	v_mul_f32_e32 v118, v121, v95
	s_nop 0
	v_addc_co_u32_e32 v59, vcc, 0, v31, vcc
	global_load_dword v165, v[58:59], off
	global_load_dwordx4 v[152:155], v[32:33], off offset:64
	global_load_dwordx4 v[160:163], v[32:33], off offset:48
	v_add_co_u32_e32 v58, vcc, s89, v30
	v_mul_f32_e32 v120, v120, v97
	s_nop 0
	v_addc_co_u32_e32 v59, vcc, 0, v31, vcc
	v_add_co_u32_e32 v60, vcc, s90, v30
	s_waitcnt vmcnt(20)
	v_mul_f32_e32 v122, v131, v99
	v_addc_co_u32_e32 v61, vcc, 0, v31, vcc
	v_add_co_u32_e32 v62, vcc, s91, v30
	v_mul_f32_e32 v124, v130, v101
	s_nop 0
	v_addc_co_u32_e32 v63, vcc, 0, v31, vcc
	v_add_co_u32_e32 v64, vcc, s92, v30
	v_mul_f32_e32 v126, v129, v103
	s_nop 0
	v_addc_co_u32_e32 v65, vcc, 0, v31, vcc
	v_add_co_u32_e32 v66, vcc, s93, v30
	v_mul_f32_e32 v128, v128, v105
	s_nop 0
	v_addc_co_u32_e32 v67, vcc, 0, v31, vcc
	v_add_co_u32_e32 v68, vcc, s94, v30
	v_mov_b32_e32 v129, v128
	s_nop 0
	v_addc_co_u32_e32 v69, vcc, 0, v31, vcc
	v_add_co_u32_e32 v70, vcc, s95, v30
	s_waitcnt vmcnt(11)
	v_mul_f32_e32 v130, v139, v107
	v_addc_co_u32_e32 v71, vcc, 0, v31, vcc
	v_add_co_u32_e32 v72, vcc, s96, v30
	v_mul_f32_e32 v132, v138, v109
	s_nop 0
	v_addc_co_u32_e32 v73, vcc, 0, v31, vcc
	global_load_dwordx4 v[168:171], v[32:33], off offset:32
	s_nop 0
	global_load_dword v59, v[58:59], off
	s_nop 0
	global_load_dword v61, v[60:61], off
	s_nop 0
	global_load_dword v63, v[62:63], off
	s_nop 0
	global_load_dwordx4 v[176:179], v[32:33], off offset:16
	s_nop 0
	global_load_dword v65, v[64:65], off
	s_nop 0
	global_load_dword v67, v[66:67], off
	s_nop 0
	global_load_dword v69, v[68:69], off
	s_nop 0
	global_load_dwordx4 v[184:187], v[32:33], off
	s_nop 0
	global_load_dword v32, v[70:71], off
	global_load_dword v33, v[72:73], off
	s_nop 0
	global_load_dword v30, v[30:31], off
	v_mul_f32_e32 v58, v15, v29
	v_mul_f32_e32 v60, v14, v35
	v_mul_f32_e32 v62, v13, v36
	v_mul_f32_e32 v64, v12, v37
	v_mul_f32_e32 v66, v11, v38
	v_mul_f32_e32 v68, v10, v39
	v_mul_f32_e32 v70, v9, v40
	v_mul_f32_e32 v72, v8, v41
	v_mul_f32_e32 v134, v137, v111
	v_mul_f32_e32 v136, v136, v113
	s_waitcnt vmcnt(22)
	v_mul_f32_e32 v138, v147, v115
	v_mul_f32_e32 v140, v146, v117
	v_mul_f32_e32 v142, v145, v119
	v_mul_f32_e32 v144, v144, v125
	v_mov_b32_e32 v145, v144
	v_mov_b32_e32 v139, v138
	v_mov_b32_e32 v137, v136
	v_mov_b32_e32 v131, v130
	v_mov_b32_e32 v125, v124
	v_mov_b32_e32 v123, v122
	v_mov_b32_e32 v121, v120
	v_mov_b32_e32 v119, v118
	v_mov_b32_e32 v117, v116
	v_mov_b32_e32 v115, v114
	v_mov_b32_e32 v113, v112
	v_mov_b32_e32 v111, v110
	v_mov_b32_e32 v109, v108
	v_mov_b32_e32 v107, v106
	v_mov_b32_e32 v105, v104
	v_mov_b32_e32 v103, v102
	v_mov_b32_e32 v101, v100
	v_mov_b32_e32 v99, v98
	v_mov_b32_e32 v97, v96
	v_mov_b32_e32 v95, v94
	v_mov_b32_e32 v93, v92
	v_mov_b32_e32 v91, v90
	v_mov_b32_e32 v77, v76
	s_waitcnt vmcnt(13)
	v_mul_f32_e32 v146, v155, v127
	v_mul_f32_e32 v148, v154, v133
	v_mul_f32_e32 v150, v153, v135
	v_mul_f32_e32 v152, v152, v141
	s_waitcnt vmcnt(12)
	v_mul_f32_e32 v154, v163, v143
	v_mul_f32_e32 v156, v162, v149
	v_mul_f32_e32 v158, v161, v151
	v_mul_f32_e32 v160, v160, v157
	v_mov_b32_e32 v161, v160
	v_mov_b32_e32 v157, v156
	v_mov_b32_e32 v155, v154
	v_mov_b32_e32 v153, v152
	v_mov_b32_e32 v151, v150
	v_mov_b32_e32 v149, v148
	v_mov_b32_e32 v147, v146
	v_mov_b32_e32 v143, v142
	v_mov_b32_e32 v141, v140
	v_mov_b32_e32 v135, v134
	v_mov_b32_e32 v133, v132
	v_mov_b32_e32 v127, v126
	v_mov_b32_e32 v75, v74
	v_mov_b32_e32 v73, v72
	v_mov_b32_e32 v71, v70
	s_waitcnt vmcnt(11)
	v_mul_f32_e32 v162, v171, v159
	v_mul_f32_e32 v164, v170, v164
	v_mul_f32_e32 v166, v169, v165
	s_waitcnt vmcnt(10)
	v_mul_f32_e32 v168, v168, v59
	s_waitcnt vmcnt(7)
	v_mul_f32_e32 v170, v179, v61
	v_mul_f32_e32 v172, v178, v63
	s_waitcnt vmcnt(6)
	v_mul_f32_e32 v174, v177, v65
	s_waitcnt vmcnt(5)
	v_mul_f32_e32 v176, v176, v67
	s_waitcnt vmcnt(3)
	v_mul_f32_e32 v178, v187, v69
	s_waitcnt vmcnt(2)
	v_mul_f32_e32 v180, v186, v32
	s_waitcnt vmcnt(1)
	v_mul_f32_e32 v182, v185, v33
	s_waitcnt vmcnt(0)
	v_mul_f32_e32 v184, v184, v30
	v_lshl_add_u64 v[186:187], s[6:7], 0, v[0:1]
	v_lshl_add_u64 v[0:1], v[2:3], 0, v[52:53]
	s_mov_b32 s6, s11
	s_lshl_b32 s11, s11, 1
	s_add_u32 s11, s11, 32
	v_mov_b32_e32 v185, v184
	v_mov_b32_e32 v183, v182
	v_mov_b32_e32 v181, v180
	v_mov_b32_e32 v179, v178
	v_mov_b32_e32 v177, v176
	v_mov_b32_e32 v175, v174
	v_mov_b32_e32 v173, v172
	v_mov_b32_e32 v171, v170
	v_mov_b32_e32 v169, v168
	v_mov_b32_e32 v167, v166
	v_mov_b32_e32 v165, v164
	v_mov_b32_e32 v163, v162
	v_mov_b32_e32 v159, v158
	v_mov_b32_e32 v69, v68
	v_mov_b32_e32 v67, v66
	v_mov_b32_e32 v65, v64
	v_mov_b32_e32 v63, v62
	v_mov_b32_e32 v61, v60
	v_mov_b32_e32 v59, v58
	v_lshl_add_u64 v[188:189], s[18:19], 0, v[0:1]
.LBB0_41:
	s_lshl_b32 s20, s6, 6
	s_lshl_b32 vcc_lo, s10, 6
	v_lshl_add_u64 v[190:191], s[20:21], 2, v[186:187]
	s_mov_b32 vcc_hi, s21
	v_lshl_add_u64 v[192:193], vcc, 2, v[186:187]
	global_load_dwordx4 v[0:3], v[190:191], off offset:48
	global_load_dwordx4 v[4:7], v[190:191], off offset:32
	global_load_dwordx4 v[8:11], v[190:191], off offset:16
	global_load_dwordx4 v[12:15], v[190:191], off
	global_load_dwordx4 v[16:19], v[192:193], off offset:48
	global_load_dwordx4 v[20:23], v[192:193], off offset:32
	global_load_dwordx4 v[24:27], v[192:193], off offset:16
	global_load_dwordx4 v[28:31], v[192:193], off
	s_add_i32 s6, s6, 4
	s_add_i32 s10, s10, 4
	s_waitcnt vmcnt(4)
	v_mov_b32_e32 v32, v12
	s_waitcnt vmcnt(0)
	v_mov_b32_e32 v33, v28
	v_pk_fma_f32 v[194:195], v[184:185], v[32:33], 0 op_sel_hi:[1,1,0]
	global_load_dwordx4 v[32:35], v[190:191], off offset:304
	global_load_dwordx4 v[36:39], v[190:191], off offset:288
	global_load_dwordx4 v[40:43], v[190:191], off offset:272
	global_load_dwordx4 v[44:47], v[190:191], off offset:256
	global_load_dwordx4 v[48:51], v[192:193], off offset:304
	global_load_dwordx4 v[212:215], v[192:193], off offset:288
	global_load_dwordx4 v[216:219], v[192:193], off offset:272
	global_load_dwordx4 v[220:223], v[192:193], off offset:256
	v_mov_b32_e32 v28, v13
	v_pk_fma_f32 v[12:13], v[182:183], v[28:29], v[194:195]
	s_waitcnt vmcnt(4)
	v_mov_b32_e32 v224, v44
	v_mov_b32_e32 v44, v14
	s_waitcnt vmcnt(0)
	v_mov_b32_e32 v225, v220
	v_pk_fma_f32 v[224:225], v[184:185], v[224:225], 0 op_sel_hi:[1,1,0]
	v_mov_b32_e32 v220, v45
	v_mov_b32_e32 v45, v30
	v_pk_fma_f32 v[28:29], v[182:183], v[220:221], v[224:225]
	v_pk_fma_f32 v[12:13], v[180:181], v[44:45], v[12:13]
	v_mov_b32_e32 v44, v46
	v_mov_b32_e32 v45, v222
	v_pk_fma_f32 v[28:29], v[180:181], v[44:45], v[28:29]
	v_mov_b32_e32 v30, v15
	v_mov_b32_e32 v222, v47
	v_pk_fma_f32 v[12:13], v[178:179], v[30:31], v[12:13]
	v_pk_fma_f32 v[14:15], v[178:179], v[222:223], v[28:29]
	v_mov_b32_e32 v28, v8
	v_mov_b32_e32 v29, v24
	v_pk_fma_f32 v[12:13], v[176:177], v[28:29], v[12:13]
	v_mov_b32_e32 v28, v40
	v_mov_b32_e32 v29, v216
	v_pk_fma_f32 v[14:15], v[176:177], v[28:29], v[14:15]
	v_mov_b32_e32 v24, v9
	v_mov_b32_e32 v216, v41
	v_pk_fma_f32 v[8:9], v[174:175], v[24:25], v[12:13]
	v_pk_fma_f32 v[12:13], v[174:175], v[216:217], v[14:15]
	v_mov_b32_e32 v14, v10
	v_mov_b32_e32 v15, v26
	v_pk_fma_f32 v[8:9], v[172:173], v[14:15], v[8:9]
	v_mov_b32_e32 v14, v42
	v_mov_b32_e32 v15, v218
	v_pk_fma_f32 v[12:13], v[172:173], v[14:15], v[12:13]
	v_mov_b32_e32 v26, v11
	v_mov_b32_e32 v218, v43
	v_pk_fma_f32 v[8:9], v[170:171], v[26:27], v[8:9]
	v_pk_fma_f32 v[10:11], v[170:171], v[218:219], v[12:13]
	v_mov_b32_e32 v12, v4
	v_mov_b32_e32 v13, v20
	v_pk_fma_f32 v[8:9], v[168:169], v[12:13], v[8:9]
	v_mov_b32_e32 v12, v36
	v_mov_b32_e32 v13, v212
	v_pk_fma_f32 v[10:11], v[168:169], v[12:13], v[10:11]
	v_mov_b32_e32 v20, v5
	v_mov_b32_e32 v212, v37
	v_pk_fma_f32 v[4:5], v[166:167], v[20:21], v[8:9]
	v_pk_fma_f32 v[8:9], v[166:167], v[212:213], v[10:11]
	v_mov_b32_e32 v10, v6
	v_mov_b32_e32 v11, v22
	v_pk_fma_f32 v[4:5], v[164:165], v[10:11], v[4:5]
	v_mov_b32_e32 v10, v38
	v_mov_b32_e32 v11, v214
	v_pk_fma_f32 v[8:9], v[164:165], v[10:11], v[8:9]
	v_mov_b32_e32 v22, v7
	v_mov_b32_e32 v214, v39
	v_pk_fma_f32 v[4:5], v[162:163], v[22:23], v[4:5]
	v_pk_fma_f32 v[6:7], v[162:163], v[214:215], v[8:9]
	v_mov_b32_e32 v8, v0
	v_mov_b32_e32 v9, v16
	v_pk_fma_f32 v[4:5], v[160:161], v[8:9], v[4:5]
	v_mov_b32_e32 v8, v32
	v_mov_b32_e32 v9, v48
	v_pk_fma_f32 v[6:7], v[160:161], v[8:9], v[6:7]
	v_mov_b32_e32 v16, v1
	v_mov_b32_e32 v48, v33
	v_pk_fma_f32 v[0:1], v[158:159], v[16:17], v[4:5]
	v_pk_fma_f32 v[4:5], v[158:159], v[48:49], v[6:7]
	v_mov_b32_e32 v6, v2
	v_mov_b32_e32 v7, v18
	v_pk_fma_f32 v[0:1], v[156:157], v[6:7], v[0:1]
	v_mov_b32_e32 v6, v34
	v_mov_b32_e32 v7, v50
	v_pk_fma_f32 v[4:5], v[156:157], v[6:7], v[4:5]
	v_mov_b32_e32 v18, v3
	v_mov_b32_e32 v50, v35
	v_pk_fma_f32 v[12:13], v[154:155], v[18:19], v[0:1]
	v_pk_fma_f32 v[194:195], v[154:155], v[50:51], v[4:5]
	global_load_dwordx4 v[0:3], v[190:191], off offset:112
	global_load_dwordx4 v[4:7], v[190:191], off offset:96
	global_load_dwordx4 v[8:11], v[190:191], off offset:80
	global_load_dwordx4 v[48:51], v[190:191], off offset:64
	global_load_dwordx4 v[16:19], v[192:193], off offset:112
	global_load_dwordx4 v[28:31], v[192:193], off offset:96
	global_load_dwordx4 v[40:43], v[192:193], off offset:80
	global_load_dwordx4 v[212:215], v[192:193], off offset:64
	s_waitcnt vmcnt(4)
	v_mov_b32_e32 v14, v48
	s_waitcnt vmcnt(0)
	v_mov_b32_e32 v15, v212
	v_pk_fma_f32 v[224:225], v[152:153], v[14:15], v[12:13]
	global_load_dwordx4 v[12:15], v[190:191], off offset:368
	global_load_dwordx4 v[24:27], v[190:191], off offset:352
	global_load_dwordx4 v[36:39], v[190:191], off offset:336
	global_load_dwordx4 v[216:219], v[190:191], off offset:320
	global_load_dwordx4 v[20:23], v[192:193], off offset:368
	global_load_dwordx4 v[32:35], v[192:193], off offset:352
	global_load_dwordx4 v[44:47], v[192:193], off offset:336
	global_load_dwordx4 v[220:223], v[192:193], off offset:320
	v_mov_b32_e32 v212, v49
	v_pk_fma_f32 v[48:49], v[150:151], v[212:213], v[224:225]
	v_mov_b32_e32 v212, v50
	v_mov_b32_e32 v213, v214
	v_pk_fma_f32 v[48:49], v[148:149], v[212:213], v[48:49]
	v_mov_b32_e32 v214, v51
	v_pk_fma_f32 v[48:49], v[146:147], v[214:215], v[48:49]
	s_waitcnt vmcnt(4)
	v_mov_b32_e32 v226, v216
	v_mov_b32_e32 v212, v218
	s_waitcnt vmcnt(0)
	v_mov_b32_e32 v227, v220
	v_pk_fma_f32 v[194:195], v[152:153], v[226:227], v[194:195]
	v_mov_b32_e32 v220, v217
	v_pk_fma_f32 v[194:195], v[150:151], v[220:221], v[194:195]
	v_mov_b32_e32 v213, v222
	v_pk_fma_f32 v[194:195], v[148:149], v[212:213], v[194:195]
	v_mov_b32_e32 v222, v219
	v_pk_fma_f32 v[50:51], v[146:147], v[222:223], v[194:195]
	v_mov_b32_e32 v194, v8
	v_mov_b32_e32 v195, v40
	v_pk_fma_f32 v[48:49], v[144:145], v[194:195], v[48:49]
	v_mov_b32_e32 v194, v36
	v_mov_b32_e32 v195, v44
	v_mov_b32_e32 v40, v9
	v_pk_fma_f32 v[50:51], v[144:145], v[194:195], v[50:51]
	v_pk_fma_f32 v[8:9], v[142:143], v[40:41], v[48:49]
	v_mov_b32_e32 v44, v37
	v_mov_b32_e32 v40, v10
	v_mov_b32_e32 v41, v42
	v_pk_fma_f32 v[36:37], v[142:143], v[44:45], v[50:51]
	v_pk_fma_f32 v[8:9], v[140:141], v[40:41], v[8:9]
	v_mov_b32_e32 v40, v38
	v_mov_b32_e32 v41, v46
	v_pk_fma_f32 v[36:37], v[140:141], v[40:41], v[36:37]
	v_mov_b32_e32 v42, v11
	v_mov_b32_e32 v46, v39
	v_pk_fma_f32 v[8:9], v[138:139], v[42:43], v[8:9]
	v_pk_fma_f32 v[10:11], v[138:139], v[46:47], v[36:37]
	v_mov_b32_e32 v36, v4
	v_mov_b32_e32 v37, v28
	v_pk_fma_f32 v[8:9], v[136:137], v[36:37], v[8:9]
	v_mov_b32_e32 v36, v24
	v_mov_b32_e32 v37, v32
	v_pk_fma_f32 v[10:11], v[136:137], v[36:37], v[10:11]
	v_mov_b32_e32 v28, v5
	v_mov_b32_e32 v32, v25
	v_pk_fma_f32 v[4:5], v[134:135], v[28:29], v[8:9]
	v_pk_fma_f32 v[8:9], v[134:135], v[32:33], v[10:11]
	v_mov_b32_e32 v10, v6
	v_mov_b32_e32 v11, v30
	v_pk_fma_f32 v[4:5], v[132:133], v[10:11], v[4:5]
	v_mov_b32_e32 v10, v26
	v_mov_b32_e32 v11, v34
	v_pk_fma_f32 v[8:9], v[132:133], v[10:11], v[8:9]
	v_mov_b32_e32 v30, v7
	v_mov_b32_e32 v34, v27
	v_pk_fma_f32 v[4:5], v[130:131], v[30:31], v[4:5]
	v_pk_fma_f32 v[6:7], v[130:131], v[34:35], v[8:9]
	v_mov_b32_e32 v8, v0
	v_mov_b32_e32 v9, v16
	v_pk_fma_f32 v[4:5], v[128:129], v[8:9], v[4:5]
	v_mov_b32_e32 v8, v12
	v_mov_b32_e32 v9, v20
	v_pk_fma_f32 v[6:7], v[128:129], v[8:9], v[6:7]
	v_mov_b32_e32 v16, v1
	v_mov_b32_e32 v20, v13
	v_pk_fma_f32 v[0:1], v[126:127], v[16:17], v[4:5]
	v_pk_fma_f32 v[4:5], v[126:127], v[20:21], v[6:7]
	v_mov_b32_e32 v6, v2
	v_mov_b32_e32 v7, v18
	v_pk_fma_f32 v[0:1], v[124:125], v[6:7], v[0:1]
	v_mov_b32_e32 v6, v14
	v_mov_b32_e32 v7, v22
	v_pk_fma_f32 v[4:5], v[124:125], v[6:7], v[4:5]
	v_mov_b32_e32 v18, v3
	v_mov_b32_e32 v22, v15
	v_pk_fma_f32 v[8:9], v[122:123], v[18:19], v[0:1]
	v_pk_fma_f32 v[194:195], v[122:123], v[22:23], v[4:5]
	global_load_dwordx4 v[0:3], v[190:191], off offset:176
	global_load_dwordx4 v[16:19], v[190:191], off offset:160
	global_load_dwordx4 v[32:35], v[190:191], off offset:144
	global_load_dwordx4 v[48:51], v[190:191], off offset:128
	global_load_dwordx4 v[4:7], v[192:193], off offset:176
	global_load_dwordx4 v[20:23], v[192:193], off offset:160
	global_load_dwordx4 v[36:39], v[192:193], off offset:144
	global_load_dwordx4 v[212:215], v[192:193], off offset:128
	s_waitcnt vmcnt(4)
	v_mov_b32_e32 v10, v48
	s_waitcnt vmcnt(0)
	v_mov_b32_e32 v11, v212
	v_pk_fma_f32 v[224:225], v[120:121], v[10:11], v[8:9]
	global_load_dwordx4 v[8:11], v[190:191], off offset:432
	global_load_dwordx4 v[24:27], v[190:191], off offset:416
	global_load_dwordx4 v[40:43], v[190:191], off offset:400
	global_load_dwordx4 v[216:219], v[190:191], off offset:384
	global_load_dwordx4 v[12:15], v[192:193], off offset:432
	global_load_dwordx4 v[28:31], v[192:193], off offset:416
	global_load_dwordx4 v[44:47], v[192:193], off offset:400
	global_load_dwordx4 v[220:223], v[192:193], off offset:384
	v_mov_b32_e32 v212, v49
	v_pk_fma_f32 v[48:49], v[118:119], v[212:213], v[224:225]
	v_mov_b32_e32 v212, v50
	v_mov_b32_e32 v213, v214
	v_pk_fma_f32 v[48:49], v[116:117], v[212:213], v[48:49]
	v_mov_b32_e32 v214, v51
	v_pk_fma_f32 v[48:49], v[114:115], v[214:215], v[48:49]
	s_waitcnt vmcnt(4)
	v_mov_b32_e32 v226, v216
	v_mov_b32_e32 v212, v218
	s_waitcnt vmcnt(0)
	v_mov_b32_e32 v227, v220
	v_pk_fma_f32 v[194:195], v[120:121], v[226:227], v[194:195]
	v_mov_b32_e32 v220, v217
	v_pk_fma_f32 v[194:195], v[118:119], v[220:221], v[194:195]
	v_mov_b32_e32 v213, v222
	v_pk_fma_f32 v[194:195], v[116:117], v[212:213], v[194:195]
	v_mov_b32_e32 v222, v219
	v_pk_fma_f32 v[50:51], v[114:115], v[222:223], v[194:195]
	v_mov_b32_e32 v194, v32
	v_mov_b32_e32 v195, v36
	v_pk_fma_f32 v[48:49], v[112:113], v[194:195], v[48:49]
	v_mov_b32_e32 v194, v40
	v_mov_b32_e32 v195, v44
	v_mov_b32_e32 v36, v33
	v_pk_fma_f32 v[50:51], v[112:113], v[194:195], v[50:51]
	v_pk_fma_f32 v[32:33], v[110:111], v[36:37], v[48:49]
	v_mov_b32_e32 v44, v41
	v_mov_b32_e32 v40, v34
	v_mov_b32_e32 v41, v38
	v_pk_fma_f32 v[36:37], v[110:111], v[44:45], v[50:51]
	v_pk_fma_f32 v[32:33], v[108:109], v[40:41], v[32:33]
	v_mov_b32_e32 v40, v42
	v_mov_b32_e32 v41, v46
	v_pk_fma_f32 v[36:37], v[108:109], v[40:41], v[36:37]
	v_mov_b32_e32 v38, v35
	v_mov_b32_e32 v46, v43
	v_pk_fma_f32 v[32:33], v[106:107], v[38:39], v[32:33]
	v_pk_fma_f32 v[34:35], v[106:107], v[46:47], v[36:37]
	v_mov_b32_e32 v36, v16
	v_mov_b32_e32 v37, v20
	v_pk_fma_f32 v[32:33], v[104:105], v[36:37], v[32:33]
	v_mov_b32_e32 v36, v24
	v_mov_b32_e32 v37, v28
	v_mov_b32_e32 v20, v17
	v_pk_fma_f32 v[34:35], v[104:105], v[36:37], v[34:35]
	v_pk_fma_f32 v[16:17], v[102:103], v[20:21], v[32:33]
	v_mov_b32_e32 v28, v25
	v_mov_b32_e32 v24, v18
	v_mov_b32_e32 v25, v22
	v_pk_fma_f32 v[20:21], v[102:103], v[28:29], v[34:35]
	v_pk_fma_f32 v[16:17], v[100:101], v[24:25], v[16:17]
	v_mov_b32_e32 v24, v26
	v_mov_b32_e32 v25, v30
	v_pk_fma_f32 v[20:21], v[100:101], v[24:25], v[20:21]
	v_mov_b32_e32 v22, v19
	v_mov_b32_e32 v30, v27
	v_pk_fma_f32 v[16:17], v[98:99], v[22:23], v[16:17]
	v_pk_fma_f32 v[18:19], v[98:99], v[30:31], v[20:21]
	v_mov_b32_e32 v20, v0
	v_mov_b32_e32 v21, v4
	v_pk_fma_f32 v[16:17], v[96:97], v[20:21], v[16:17]
	v_mov_b32_e32 v20, v8
	v_mov_b32_e32 v21, v12
	v_mov_b32_e32 v4, v1
	v_pk_fma_f32 v[18:19], v[96:97], v[20:21], v[18:19]
	v_pk_fma_f32 v[0:1], v[94:95], v[4:5], v[16:17]
	v_mov_b32_e32 v12, v9
	v_mov_b32_e32 v8, v2
	v_mov_b32_e32 v9, v6
	v_pk_fma_f32 v[4:5], v[94:95], v[12:13], v[18:19]
	v_pk_fma_f32 v[0:1], v[92:93], v[8:9], v[0:1]
	v_mov_b32_e32 v8, v10
	v_mov_b32_e32 v9, v14
	v_pk_fma_f32 v[4:5], v[92:93], v[8:9], v[4:5]
	v_mov_b32_e32 v6, v3
	v_mov_b32_e32 v14, v11
	v_pk_fma_f32 v[8:9], v[90:91], v[6:7], v[0:1]
	v_pk_fma_f32 v[194:195], v[90:91], v[14:15], v[4:5]
	global_load_dwordx4 v[0:3], v[190:191], off offset:240
	global_load_dwordx4 v[16:19], v[190:191], off offset:224
	global_load_dwordx4 v[32:35], v[190:191], off offset:208
	global_load_dwordx4 v[48:51], v[190:191], off offset:192
	global_load_dwordx4 v[4:7], v[192:193], off offset:240
	global_load_dwordx4 v[20:23], v[192:193], off offset:224
	global_load_dwordx4 v[36:39], v[192:193], off offset:208
	global_load_dwordx4 v[212:215], v[192:193], off offset:192
	s_waitcnt vmcnt(4)
	v_mov_b32_e32 v10, v48
	s_waitcnt vmcnt(0)
	v_mov_b32_e32 v11, v212
	v_pk_fma_f32 v[220:221], v[88:89], v[10:11], v[8:9]
	global_load_dwordx4 v[8:11], v[190:191], off offset:496
	global_load_dwordx4 v[24:27], v[190:191], off offset:480
	global_load_dwordx4 v[40:43], v[190:191], off offset:464
	global_load_dwordx4 v[216:219], v[190:191], off offset:448
	global_load_dwordx4 v[12:15], v[192:193], off offset:496
	global_load_dwordx4 v[28:31], v[192:193], off offset:480
	global_load_dwordx4 v[44:47], v[192:193], off offset:464
	s_nop 0
	global_load_dwordx4 v[190:193], v[192:193], off offset:448
	v_mov_b32_e32 v212, v49
	v_pk_fma_f32 v[48:49], v[86:87], v[212:213], v[220:221]
	s_waitcnt vmcnt(4)
	v_mov_b32_e32 v222, v216
	s_waitcnt vmcnt(0)
	v_mov_b32_e32 v223, v190
	v_pk_fma_f32 v[194:195], v[88:89], v[222:223], v[194:195]
	v_mov_b32_e32 v190, v217
	v_pk_fma_f32 v[190:191], v[86:87], v[190:191], v[194:195]
	v_mov_b32_e32 v194, v50
	v_mov_b32_e32 v195, v214
	v_pk_fma_f32 v[48:49], v[84:85], v[194:195], v[48:49]
	v_mov_b32_e32 v194, v218
	v_mov_b32_e32 v195, v192
	v_pk_fma_f32 v[190:191], v[84:85], v[194:195], v[190:191]
	v_mov_b32_e32 v214, v51
	v_mov_b32_e32 v192, v219
	v_pk_fma_f32 v[48:49], v[82:83], v[214:215], v[48:49]
	v_pk_fma_f32 v[50:51], v[82:83], v[192:193], v[190:191]
	v_mov_b32_e32 v190, v32
	v_mov_b32_e32 v191, v36
	v_pk_fma_f32 v[48:49], v[80:81], v[190:191], v[48:49]
	v_mov_b32_e32 v190, v40
	v_mov_b32_e32 v191, v44
	v_mov_b32_e32 v36, v33
	v_pk_fma_f32 v[50:51], v[80:81], v[190:191], v[50:51]
	v_pk_fma_f32 v[32:33], v[78:79], v[36:37], v[48:49]
	v_mov_b32_e32 v44, v41
	v_mov_b32_e32 v40, v34
	v_mov_b32_e32 v41, v38
	v_pk_fma_f32 v[36:37], v[78:79], v[44:45], v[50:51]
	v_pk_fma_f32 v[32:33], v[76:77], v[40:41], v[32:33]
	v_mov_b32_e32 v40, v42
	v_mov_b32_e32 v41, v46
	v_pk_fma_f32 v[36:37], v[76:77], v[40:41], v[36:37]
	v_mov_b32_e32 v38, v35
	v_mov_b32_e32 v46, v43
	v_pk_fma_f32 v[32:33], v[74:75], v[38:39], v[32:33]
	v_pk_fma_f32 v[34:35], v[74:75], v[46:47], v[36:37]
	v_mov_b32_e32 v36, v16
	v_mov_b32_e32 v37, v20
	v_pk_fma_f32 v[32:33], v[72:73], v[36:37], v[32:33]
	v_mov_b32_e32 v36, v24
	v_mov_b32_e32 v37, v28
	v_mov_b32_e32 v20, v17
	v_pk_fma_f32 v[34:35], v[72:73], v[36:37], v[34:35]
	v_pk_fma_f32 v[16:17], v[70:71], v[20:21], v[32:33]
	v_mov_b32_e32 v28, v25
	v_mov_b32_e32 v24, v18
	v_mov_b32_e32 v25, v22
	v_pk_fma_f32 v[20:21], v[70:71], v[28:29], v[34:35]
	v_pk_fma_f32 v[16:17], v[68:69], v[24:25], v[16:17]
	v_mov_b32_e32 v24, v26
	v_mov_b32_e32 v25, v30
	v_pk_fma_f32 v[20:21], v[68:69], v[24:25], v[20:21]
	v_mov_b32_e32 v22, v19
	v_mov_b32_e32 v30, v27
	v_pk_fma_f32 v[16:17], v[66:67], v[22:23], v[16:17]
	v_pk_fma_f32 v[18:19], v[66:67], v[30:31], v[20:21]
	v_mov_b32_e32 v20, v0
	v_mov_b32_e32 v21, v4
	v_pk_fma_f32 v[16:17], v[64:65], v[20:21], v[16:17]
	v_mov_b32_e32 v20, v8
	v_mov_b32_e32 v21, v12
	v_mov_b32_e32 v4, v1
	v_pk_fma_f32 v[18:19], v[64:65], v[20:21], v[18:19]
	v_pk_fma_f32 v[0:1], v[62:63], v[4:5], v[16:17]
	v_mov_b32_e32 v12, v9
	v_mov_b32_e32 v8, v2
	v_mov_b32_e32 v9, v6
	v_pk_fma_f32 v[4:5], v[62:63], v[12:13], v[18:19]
	v_pk_fma_f32 v[0:1], v[60:61], v[8:9], v[0:1]
	v_mov_b32_e32 v8, v10
	v_mov_b32_e32 v9, v14
	v_mov_b32_e32 v6, v3
	v_pk_fma_f32 v[4:5], v[60:61], v[8:9], v[4:5]
	v_pk_fma_f32 v[0:1], v[58:59], v[6:7], v[0:1]
	v_mov_b32_e32 v14, v11
	v_pk_fma_f32 v[2:3], v[58:59], v[14:15], v[4:5]
	v_and_b32_sdwa v4, v1, v211 dst_sel:DWORD dst_unused:UNUSED_PAD src0_sel:WORD_1 src1_sel:DWORD
	v_and_b32_sdwa v5, v0, v211 dst_sel:DWORD dst_unused:UNUSED_PAD src0_sel:WORD_1 src1_sel:DWORD
	v_add3_u32 v0, v0, v5, s27
	v_add3_u32 v1, v1, v4, s27
	v_and_b32_sdwa v4, v3, v211 dst_sel:DWORD dst_unused:UNUSED_PAD src0_sel:WORD_1 src1_sel:DWORD
	v_and_b32_sdwa v5, v2, v211 dst_sel:DWORD dst_unused:UNUSED_PAD src0_sel:WORD_1 src1_sel:DWORD
	v_add3_u32 v3, v3, v4, s27
	v_add3_u32 v2, v2, v5, s27
	v_and_b32_e32 v3, 0xffff0000, v3
	v_and_b32_e32 v2, 0xffff0000, v2
	v_or_b32_sdwa v1, v3, v1 dst_sel:DWORD dst_unused:UNUSED_PAD src0_sel:DWORD src1_sel:WORD_1
	v_or_b32_sdwa v0, v2, v0 dst_sel:DWORD dst_unused:UNUSED_PAD src0_sel:DWORD src1_sel:WORD_1
	v_lshl_add_u64 v[2:3], v[188:189], 0, s[4:5]
	s_add_u32 s4, s4, 8
	s_addc_u32 s5, s5, 0
	s_cmp_eq_u32 s4, s11
	global_store_dwordx2 v[2:3], v[0:1], off
	s_cbranch_scc0 .LBB0_41
	s_branch .LBB0_20
